# grid barrier: released workgroups poll the cross-XCC generation word directly (one hop less per barrier)
# speedup vs baseline: 1.0087x; 1.0002x over previous
.LBB0_132:
	s_add_i32 s12, s3, 0x500
	s_mov_b32 s13, 0
	s_lshl_b64 s[4:5], s[12:13], 2
	s_add_u32 s4, s8, s4
	s_addc_u32 s5, s9, s5
	v_mov_b32_e32 v1, 1
	v_mov_b64_e32 v[6:7], s[4:5]
	flat_atomic_add v1, v[6:7], v1 sc0
	v_cvt_f32_u32_e32 v3, v4
	v_sub_u32_e32 v5, 0, v4
	v_rcp_iflag_f32_e32 v3, v3
	s_nop 0
	v_mul_f32_e32 v3, 0x4f7ffffe, v3
	v_cvt_u32_f32_e32 v3, v3
	v_mul_lo_u32 v5, v5, v3
	v_mul_hi_u32 v5, v3, v5
	v_add_u32_e32 v3, v3, v5
	s_waitcnt vmcnt(0) lgkmcnt(0)
	v_mul_hi_u32 v3, v1, v3
	v_mul_lo_u32 v5, v3, v4
	v_add_u32_e32 v6, 1, v1
	v_sub_u32_e32 v1, v1, v5
	v_add_u32_e32 v7, 1, v3
	v_cmp_ge_u32_e32 vcc, v1, v4
	v_sub_u32_e32 v5, v1, v4
	s_nop 0
	v_cndmask_b32_e32 v3, v3, v7, vcc
	v_cndmask_b32_e32 v1, v1, v5, vcc
	v_add_u32_e32 v5, 1, v3
	v_cmp_ge_u32_e32 vcc, v1, v4
	s_nop 1
	v_cndmask_b32_e32 v1, v3, v5, vcc
	v_mad_u64_u32 v[4:5], s[4:5], v4, v1, v[4:5]
	v_cmp_ne_u32_e32 vcc, v6, v4
	s_and_saveexec_b64 s[4:5], vcc
	s_xor_b64 s[10:11], exec, s[4:5]
	s_cbranch_execz .LBB0_145
	s_add_i32 s12, s3, 0x900
	s_lshl_b64 s[4:5], s[12:13], 2
	s_add_u32 s14, s8, 0x3500
	s_addc_u32 s15, s9, 0
	v_mov_b64_e32 v[2:3], s[14:15]
	flat_load_dword v2, v[2:3] sc1
	s_waitcnt vmcnt(0) lgkmcnt(0)
	v_cmp_eq_u32_e32 vcc, v2, v1
	s_and_saveexec_b64 s[12:13], vcc
	s_cbranch_execz .LBB0_144
	s_mov_b32 s30, 1
	s_mov_b64 s[16:17], 0
	s_branch .LBB0_136

.LBB0_1772:
	s_add_i32 s10, s3, 0x500
	s_mov_b32 s11, 0
	s_lshl_b64 s[4:5], s[10:11], 2
	s_add_u32 s4, s72, s4
	s_addc_u32 s5, s73, s5
	v_mov_b32_e32 v1, 1
	v_mov_b64_e32 v[6:7], s[4:5]
	flat_atomic_add v1, v[6:7], v1 sc0
	v_cvt_f32_u32_e32 v3, v4
	v_sub_u32_e32 v5, 0, v4
	v_rcp_iflag_f32_e32 v3, v3
	s_nop 0
	v_mul_f32_e32 v3, 0x4f7ffffe, v3
	v_cvt_u32_f32_e32 v3, v3
	v_mul_lo_u32 v5, v5, v3
	v_mul_hi_u32 v5, v3, v5
	v_add_u32_e32 v3, v3, v5
	s_waitcnt vmcnt(0) lgkmcnt(0)
	v_mul_hi_u32 v3, v1, v3
	v_mul_lo_u32 v5, v3, v4
	v_add_u32_e32 v6, 1, v1
	v_sub_u32_e32 v1, v1, v5
	v_add_u32_e32 v7, 1, v3
	v_cmp_ge_u32_e32 vcc, v1, v4
	v_sub_u32_e32 v5, v1, v4
	s_nop 0
	v_cndmask_b32_e32 v3, v3, v7, vcc
	v_cndmask_b32_e32 v1, v1, v5, vcc
	v_add_u32_e32 v5, 1, v3
	v_cmp_ge_u32_e32 vcc, v1, v4
	s_nop 1
	v_cndmask_b32_e32 v1, v3, v5, vcc
	v_mad_u64_u32 v[4:5], s[4:5], v4, v1, v[4:5]
	v_cmp_ne_u32_e32 vcc, v6, v4
	s_and_saveexec_b64 s[4:5], vcc
	s_xor_b64 s[8:9], exec, s[4:5]
	s_cbranch_execz .LBB0_1785
	s_add_i32 s10, s3, 0x900
	s_lshl_b64 s[4:5], s[10:11], 2
	s_add_u32 s12, s72, 0x3500
	s_addc_u32 s13, s73, 0
	v_mov_b64_e32 v[2:3], s[12:13]
	flat_load_dword v2, v[2:3] sc1
	s_waitcnt vmcnt(0) lgkmcnt(0)
	v_cmp_eq_u32_e32 vcc, v2, v1
	s_and_saveexec_b64 s[10:11], vcc
	s_cbranch_execz .LBB0_1784
	s_mov_b32 s28, 1
	s_mov_b64 s[14:15], 0
	s_branch .LBB0_1776
